# latent local attention tiles: column-mask penalty and running max folded into QK MFMA C operand (32 fewer VALU per local tile)
# speedup vs baseline: 1.0207x; 1.0019x over previous
.LBB0_613:
	s_or_b64 exec, exec, s[10:11]
	s_ashr_i32 s14, s22, 5
	s_bfe_u32 s13, s22, 0x40001
	s_lshl_b32 s12, s14, 10
	s_lshl_b32 s10, s13, 6
	s_lshl_b32 s11, s22, 5
	s_and_b32 s23, s11, 32
	s_or_b32 s10, s12, s10
	s_or_b32 s10, s10, s23
	s_addk_i32 s10, 0x2000
	s_ashr_i32 s11, s10, 31
	v_lshl_add_u64 v[2:3], v[134:135], 0, s[10:11]
	s_lshl_b32 s11, s14, 4
	s_add_i32 s14, s18, s11
	s_ashr_i32 s15, s14, 31
	v_lshlrev_b64 v[2:3], 7, v[2:3]
	s_lshl_b64 s[14:15], s[14:15], 15
	v_lshl_add_u64 v[2:3], v[136:137], 0, v[2:3]
	v_lshl_add_u64 v[166:167], v[148:149], 0, s[14:15]
	v_lshl_add_u64 v[168:169], v[150:151], 0, s[14:15]
	global_load_dwordx4 v[64:67], v[2:3], off
	global_load_dwordx4 v[68:71], v[2:3], off offset:32
	global_load_dwordx4 v[72:75], v[2:3], off offset:64
	global_load_dwordx4 v[76:79], v[2:3], off offset:96
	global_load_dwordx4 v[104:107], v[166:167], off
	global_load_dwordx4 v[100:103], v[166:167], off offset:1024
	global_load_dwordx4 v[108:111], v[166:167], off offset:2048
	global_load_dwordx4 v[112:115], v[166:167], off offset:3072
	global_load_dwordx4 v[92:95], v[168:169], off
	global_load_dwordx4 v[80:83], v[168:169], off offset:1024
	global_load_dwordx4 v[84:87], v[168:169], off offset:2048
	global_load_dwordx4 v[88:91], v[168:169], off offset:3072
	v_mov_b32_e32 v14, v1
	v_mov_b32_e32 v15, v1
	v_mov_b32_e32 v0, v1
	v_mov_b32_e32 v2, v1
	v_mov_b32_e32 v3, v1
	v_mov_b32_e32 v4, v1
	v_mov_b32_e32 v5, v1
	v_mov_b32_e32 v6, v1
	v_mov_b32_e32 v7, v1
	v_mov_b32_e32 v8, v1
	v_mov_b32_e32 v9, v1
	v_mov_b32_e32 v10, v1
	v_mov_b32_e32 v11, v1
	v_mov_b32_e32 v12, v1
	v_mov_b32_e32 v13, v1
	v_mov_b64_e32 v[30:31], v[14:15]
	v_mov_b64_e32 v[46:47], v[14:15]
	s_lshr_b32 s11, s22, 1
	v_lshl_add_u64 v[170:171], v[154:155], 0, s[14:15]
	v_lshl_add_u64 v[172:173], v[156:157], 0, s[14:15]
	s_mov_b32 s24, 0
	v_mov_b32_e32 v224, 0
	v_mov_b32_e32 v192, 0xf149f2ca
	s_movk_i32 s25, 0x1000
	v_mov_b64_e32 v[28:29], v[12:13]
	v_mov_b64_e32 v[26:27], v[10:11]
	v_mov_b64_e32 v[24:25], v[8:9]
	v_mov_b64_e32 v[22:23], v[6:7]
	v_mov_b64_e32 v[20:21], v[4:5]
	v_mov_b64_e32 v[18:19], v[2:3]
	v_mov_b64_e32 v[16:17], v[0:1]
	v_mov_b64_e32 v[44:45], v[12:13]
	v_mov_b64_e32 v[42:43], v[10:11]
	v_mov_b64_e32 v[40:41], v[8:9]
	v_mov_b64_e32 v[38:39], v[6:7]
	v_mov_b64_e32 v[36:37], v[4:5]
	v_mov_b64_e32 v[34:35], v[2:3]
	v_mov_b64_e32 v[32:33], v[0:1]
	s_branch .LBB0_615
.LBB0_614:
	v_sub_f32_e32 v14, v48, v192
	v_exp_f32_e32 v14, v14
	v_sub_f32_e32 v48, v49, v192
	v_exp_f32_e32 v48, v48
	v_sub_f32_e32 v49, v50, v192
	v_exp_f32_e32 v49, v49
	v_sub_f32_e32 v50, v51, v192
	v_exp_f32_e32 v50, v50
	v_sub_f32_e32 v51, v52, v192
	v_sub_f32_e32 v52, v53, v192
	v_sub_f32_e32 v53, v54, v192
	v_sub_f32_e32 v54, v55, v192
	v_add_f32_e32 v15, 0, v14
	v_exp_f32_e32 v51, v51
	v_exp_f32_e32 v52, v52
	v_exp_f32_e32 v53, v53
	v_exp_f32_e32 v54, v54
	v_add_f32_e32 v15, v48, v15
	v_add_f32_e32 v15, v49, v15
	v_add_f32_e32 v15, v50, v15
	v_add_f32_e32 v15, v51, v15
	v_cvt_pk_bf16_f32 v48, v14, v48
	v_cvt_pk_bf16_f32 v49, v49, v50
	v_cvt_pk_bf16_f32 v50, v51, v52
	v_cvt_pk_bf16_f32 v51, v53, v54
	v_sub_f32_e32 v55, v56, v192
	v_sub_f32_e32 v56, v57, v192
	s_waitcnt vmcnt(11)
	v_mfma_f32_32x32x16_bf16 v[32:47], v[96:99], v[48:51], v[32:47]
	v_sub_f32_e32 v57, v58, v192
	v_sub_f32_e32 v58, v59, v192
	v_sub_f32_e32 v59, v60, v192
	v_sub_f32_e32 v60, v61, v192
	v_sub_f32_e32 v61, v62, v192
	v_sub_f32_e32 v62, v63, v192
	v_exp_f32_e32 v55, v55
	s_waitcnt vmcnt(9)
	v_mfma_f32_32x32x16_bf16 v[16:31], v[6:9], v[48:51], v[16:31]
	v_exp_f32_e32 v56, v56
	v_exp_f32_e32 v57, v57
	v_exp_f32_e32 v58, v58
	v_exp_f32_e32 v59, v59
	v_exp_f32_e32 v60, v60
	v_exp_f32_e32 v61, v61
	v_exp_f32_e32 v62, v62
	v_add_f32_e32 v15, v52, v15
	v_add_f32_e32 v15, v53, v15
	v_add_f32_e32 v15, v54, v15
	v_add_f32_e32 v15, v55, v15
	v_cvt_pk_bf16_f32 v52, v55, v56
	v_cvt_pk_bf16_f32 v53, v57, v58
	v_cvt_pk_bf16_f32 v54, v59, v60
	v_cvt_pk_bf16_f32 v55, v61, v62
	v_add_f32_e32 v15, v56, v15
	v_add_f32_e32 v15, v57, v15
	v_mfma_f32_32x32x16_bf16 v[32:47], v[10:13], v[52:55], v[32:47]
	v_add_f32_e32 v15, v58, v15
	v_add_f32_e32 v15, v59, v15
	v_add_f32_e32 v15, v60, v15
	v_add_f32_e32 v15, v61, v15
	v_add_f32_e32 v15, v62, v15
	s_add_i32 s24, s24, 2
	v_add_f32_e32 v224, v0, v15
	s_waitcnt vmcnt(8)
	v_mfma_f32_32x32x16_bf16 v[16:31], v[2:5], v[52:55], v[16:31]
	s_addk_i32 s25, 0x1000
	v_lshl_add_u64 v[170:171], v[170:171], 0, s[78:79]
	v_lshl_add_u64 v[172:173], v[172:173], 0, s[78:79]
	s_andn2_b64 vcc, exec, s[14:15]
	s_cbranch_vccz .LBB0_619
.LBB0_615:
	global_load_dwordx4 v[116:119], v[172:173], off offset:-2048
	global_load_dwordx4 v[120:123], v[172:173], off offset:-1024
	global_load_dwordx4 v[124:127], v[172:173], off
	global_load_dwordx4 v[128:131], v[172:173], off offset:1024
	global_load_dwordx4 v[96:99], v[170:171], off offset:-2048
	global_load_dwordx4 v[10:13], v[170:171], off offset:-1024
	global_load_dwordx4 v[6:9], v[170:171], off
	global_load_dwordx4 v[2:5], v[170:171], off offset:1024
	s_waitcnt vmcnt(15)
	v_mfma_f32_32x32x16_bf16 v[48:63], v[104:107], v[64:67], 0
	s_waitcnt vmcnt(14)
	v_mfma_f32_32x32x16_bf16 v[48:63], v[100:103], v[68:71], v[48:63]
	s_waitcnt vmcnt(13)
	v_mfma_f32_32x32x16_bf16 v[48:63], v[108:111], v[72:75], v[48:63]
	s_waitcnt vmcnt(12)
	v_mfma_f32_32x32x16_bf16 v[48:63], v[112:115], v[76:79], v[48:63]
	s_nop 11
	v_max_f32_e32 v0, v49, v49
	v_max_f32_e32 v14, v48, v48
	v_max_f32_e32 v0, v14, v0
	v_max3_f32 v0, v0, v50, v51
	v_max3_f32 v0, v0, v52, v53
	v_max3_f32 v0, v0, v54, v55
	v_max3_f32 v0, v0, v56, v57
	v_max3_f32 v0, v0, v58, v59
	v_max3_f32 v0, v0, v60, v61
	v_max3_f32 v0, v0, v62, v63
	v_mov_b32_e32 v14, v0
	s_nop 1
	v_permlane32_swap_b32_e32 v0, v14
	v_max_f32_e32 v14, v14, v14
	v_max_f32_e32 v0, v0, v0
	v_max_f32_e32 v0, v0, v14
	v_sub_f32_e32 v14, v0, v192
	v_cmp_lt_f32_e32 vcc, s90, v14
	s_cbranch_vccz .LBB0_617
	v_max_f32_e32 v0, v0, v0
	v_max_f32_e32 v14, v192, v192
	v_max_f32_e32 v14, v14, v0
	v_sub_f32_e32 v0, v192, v14
	v_exp_f32_e32 v0, v0
	v_mov_b32_e32 v192, v14
	v_mul_f32_e32 v224, v224, v0
	v_pk_mul_f32 v[46:47], v[46:47], v[0:1] op_sel_hi:[1,0]
	v_pk_mul_f32 v[44:45], v[44:45], v[0:1] op_sel_hi:[1,0]
	v_pk_mul_f32 v[42:43], v[42:43], v[0:1] op_sel_hi:[1,0]
	v_pk_mul_f32 v[40:41], v[40:41], v[0:1] op_sel_hi:[1,0]
	v_pk_mul_f32 v[38:39], v[38:39], v[0:1] op_sel_hi:[1,0]
	v_pk_mul_f32 v[36:37], v[36:37], v[0:1] op_sel_hi:[1,0]
	v_pk_mul_f32 v[34:35], v[34:35], v[0:1] op_sel_hi:[1,0]
	v_pk_mul_f32 v[32:33], v[32:33], v[0:1] op_sel_hi:[1,0]
	v_pk_mul_f32 v[30:31], v[30:31], v[0:1] op_sel_hi:[1,0]
	v_pk_mul_f32 v[28:29], v[28:29], v[0:1] op_sel_hi:[1,0]
	v_pk_mul_f32 v[26:27], v[26:27], v[0:1] op_sel_hi:[1,0]
	v_pk_mul_f32 v[24:25], v[24:25], v[0:1] op_sel_hi:[1,0]
	v_pk_mul_f32 v[22:23], v[22:23], v[0:1] op_sel_hi:[1,0]
	v_pk_mul_f32 v[20:21], v[20:21], v[0:1] op_sel_hi:[1,0]
	v_pk_mul_f32 v[18:19], v[18:19], v[0:1] op_sel_hi:[1,0]
	v_pk_mul_f32 v[16:17], v[16:17], v[0:1] op_sel_hi:[1,0]
.LBB0_617:
	v_sub_f32_e32 v0, v48, v192
	v_sub_f32_e32 v48, v50, v192
	v_sub_f32_e32 v15, v49, v192
	v_exp_f32_e32 v49, v48
	v_sub_f32_e32 v48, v51, v192
	v_exp_f32_e32 v50, v48
	v_sub_f32_e32 v48, v52, v192
	v_exp_f32_e32 v51, v48
	v_sub_f32_e32 v48, v53, v192
	v_exp_f32_e32 v52, v48
	v_sub_f32_e32 v48, v54, v192
	v_exp_f32_e32 v53, v48
	v_sub_f32_e32 v48, v55, v192
	v_exp_f32_e32 v14, v0
	v_exp_f32_e32 v54, v48
	v_sub_f32_e32 v48, v56, v192
	v_exp_f32_e32 v15, v15
	v_exp_f32_e32 v55, v48
	v_sub_f32_e32 v48, v57, v192
	v_exp_f32_e32 v56, v48
	v_sub_f32_e32 v48, v58, v192
	v_exp_f32_e32 v57, v48
	v_sub_f32_e32 v48, v59, v192
	v_add_f32_e32 v0, 0, v14
	v_exp_f32_e32 v58, v48
	v_sub_f32_e32 v48, v60, v192
	v_add_f32_e32 v0, v15, v0
	v_exp_f32_e32 v59, v48
	v_sub_f32_e32 v48, v61, v192
	v_add_f32_e32 v0, v49, v0
	v_exp_f32_e32 v60, v48
	v_sub_f32_e32 v48, v62, v192
	v_add_f32_e32 v0, v50, v0
	v_exp_f32_e32 v61, v48
	v_sub_f32_e32 v48, v63, v192
	v_add_f32_e32 v0, v51, v0
	v_exp_f32_e32 v62, v48
	v_cvt_pk_bf16_f32 v48, v14, v15
	v_cvt_pk_bf16_f32 v49, v49, v50
	v_cvt_pk_bf16_f32 v50, v51, v52
	v_cvt_pk_bf16_f32 v51, v53, v54
	s_cmp_gt_u32 s24, 5
	s_cselect_b64 s[14:15], -1, 0
	s_waitcnt vmcnt(11)
	v_mfma_f32_32x32x16_bf16 v[32:47], v[92:95], v[48:51], v[32:47]
	s_cmp_lt_u32 s24, 6
	v_add_f32_e32 v0, v52, v0
	s_cselect_b32 s70, s25, 0
	v_add_f32_e32 v0, v53, v0
	s_lshl_b64 s[26:27], s[70:71], 1
	v_add_f32_e32 v0, v54, v0
	v_lshl_add_u64 v[14:15], v[166:167], 0, s[26:27]
	s_waitcnt vmcnt(9)
	v_mfma_f32_32x32x16_bf16 v[16:31], v[84:87], v[48:51], v[16:31]
	v_add_f32_e32 v0, v55, v0
	v_cvt_pk_bf16_f32 v52, v55, v56
	v_cvt_pk_bf16_f32 v53, v57, v58
	v_cvt_pk_bf16_f32 v54, v59, v60
	v_cvt_pk_bf16_f32 v55, v61, v62
	global_load_dwordx4 v[104:107], v[14:15], off
	global_load_dwordx4 v[100:103], v[14:15], off offset:1024
	global_load_dwordx4 v[108:111], v[14:15], off offset:2048
	global_load_dwordx4 v[112:115], v[14:15], off offset:3072
	v_lshl_add_u64 v[14:15], v[168:169], 0, s[26:27]
	v_mfma_f32_32x32x16_bf16 v[32:47], v[80:83], v[52:55], v[32:47]
	v_add_f32_e32 v0, v56, v0
	v_add_f32_e32 v0, v57, v0
	v_add_f32_e32 v0, v58, v0
	v_add_f32_e32 v0, v59, v0
	v_add_f32_e32 v0, v60, v0
	v_add_f32_e32 v0, v61, v0
	v_add_f32_e32 v0, v62, v0
	s_waitcnt vmcnt(12)
	v_mfma_f32_32x32x16_bf16 v[16:31], v[88:91], v[52:55], v[16:31]
	global_load_dwordx4 v[92:95], v[14:15], off
	global_load_dwordx4 v[80:83], v[14:15], off offset:1024
	global_load_dwordx4 v[84:87], v[14:15], off offset:2048
	global_load_dwordx4 v[88:91], v[14:15], off offset:3072
	v_add_f32_e32 v0, v224, v0
	s_waitcnt vmcnt(15)
	v_mfma_f32_32x32x16_bf16 v[48:63], v[116:119], v[64:67], 0
	s_waitcnt vmcnt(14)
	v_mfma_f32_32x32x16_bf16 v[48:63], v[120:123], v[68:71], v[48:63]
	s_waitcnt vmcnt(13)
	v_mfma_f32_32x32x16_bf16 v[48:63], v[124:127], v[72:75], v[48:63]
	s_waitcnt vmcnt(12)
	v_mfma_f32_32x32x16_bf16 v[48:63], v[128:131], v[76:79], v[48:63]
	s_nop 11
	v_max_f32_e32 v14, v49, v49
	v_max_f32_e32 v15, v48, v48
	v_max_f32_e32 v14, v15, v14
	v_max3_f32 v14, v14, v50, v51
	v_max3_f32 v14, v14, v52, v53
	v_max3_f32 v14, v14, v54, v55
	v_max3_f32 v14, v14, v56, v57
	v_max3_f32 v14, v14, v58, v59
	v_max3_f32 v14, v14, v60, v61
	v_max3_f32 v14, v14, v62, v63
	v_mov_b32_e32 v15, v14
	s_nop 1
	v_permlane32_swap_b32_e32 v14, v15
	v_max_f32_e32 v15, v15, v15
	v_max_f32_e32 v14, v14, v14
	v_max_f32_e32 v14, v14, v15
	v_sub_f32_e32 v15, v14, v192
	v_cmp_lt_f32_e32 vcc, s90, v15
	s_cbranch_vccz .LBB0_614
	v_max_f32_e32 v14, v14, v14
	v_max_f32_e32 v15, v192, v192
	v_max_f32_e32 v15, v15, v14
	v_sub_f32_e32 v14, v192, v15
	v_exp_f32_e32 v14, v14
	v_mov_b32_e32 v192, v15
	v_mul_f32_e32 v0, v0, v14
	v_pk_mul_f32 v[46:47], v[46:47], v[14:15] op_sel_hi:[1,0]
	v_pk_mul_f32 v[44:45], v[44:45], v[14:15] op_sel_hi:[1,0]
	v_pk_mul_f32 v[42:43], v[42:43], v[14:15] op_sel_hi:[1,0]
	v_pk_mul_f32 v[40:41], v[40:41], v[14:15] op_sel_hi:[1,0]
	v_pk_mul_f32 v[38:39], v[38:39], v[14:15] op_sel_hi:[1,0]
	v_pk_mul_f32 v[36:37], v[36:37], v[14:15] op_sel_hi:[1,0]
	v_pk_mul_f32 v[34:35], v[34:35], v[14:15] op_sel_hi:[1,0]
	v_pk_mul_f32 v[32:33], v[32:33], v[14:15] op_sel_hi:[1,0]
	v_pk_mul_f32 v[30:31], v[30:31], v[14:15] op_sel_hi:[1,0]
	v_pk_mul_f32 v[28:29], v[28:29], v[14:15] op_sel_hi:[1,0]
	v_pk_mul_f32 v[26:27], v[26:27], v[14:15] op_sel_hi:[1,0]
	v_pk_mul_f32 v[24:25], v[24:25], v[14:15] op_sel_hi:[1,0]
	v_pk_mul_f32 v[22:23], v[22:23], v[14:15] op_sel_hi:[1,0]
	v_pk_mul_f32 v[20:21], v[20:21], v[14:15] op_sel_hi:[1,0]
	v_pk_mul_f32 v[18:19], v[18:19], v[14:15] op_sel_hi:[1,0]
	v_pk_mul_f32 v[16:17], v[16:17], v[14:15] op_sel_hi:[1,0]
	s_branch .LBB0_614
.LBB0_619:
	v_mov_b32_e32 v172, v192
	s_and_b32 s11, s11, 15
	s_max_i32 s14, s11, 4
	s_and_b32 s24, s21, 32
	s_add_i32 s14, s14, -4
	v_subrev_u32_e32 v0, s24, v191
	s_min_u32 s15, s14, 8
	v_lshlrev_b32_e32 v0, 2, v0
	s_lshl_b32 s11, s11, 9
	v_lshl_add_u32 v0, s15, 9, v0
	s_cmp_lt_u32 s14, 8
	v_subrev_u32_e32 v0, s11, v0
	s_cselect_b32 s11, s14, 8
	s_max_i32 s13, s13, 4
	s_add_i32 s13, s13, -4
	s_lshl_b32 s11, s11, 13
	s_min_u32 s14, s13, 8
	s_ashr_i32 s13, s12, 31
	v_or_b32_e32 v2, s23, v174
	s_add_u32 s23, s8, s12
	s_addc_u32 s15, s9, s13
	s_lshl_b32 s14, s14, 6
	s_or_b32 s14, s23, s14
	v_max_i32_e32 v2, 8, v2
	s_lshl_b64 s[14:15], s[14:15], 7
	v_add_u32_e32 v2, -8, v2
	v_lshl_add_u64 v[14:15], v[138:139], 0, s[14:15]
	v_lshl_add_u64 v[166:167], v[140:141], 0, s[14:15]
	v_min_u32_e32 v48, 48, v2
	global_load_dwordx4 v[100:103], v[14:15], off
	global_load_dwordx4 v[104:107], v[14:15], off offset:1024
	global_load_dwordx4 v[108:111], v[14:15], off offset:2048
	global_load_dwordx4 v[112:115], v[14:15], off offset:3072
	global_load_dwordx4 v[80:83], v[166:167], off
	global_load_dwordx4 v[6:9], v[166:167], off offset:1024
	global_load_dwordx4 v[10:13], v[166:167], off offset:2048
	global_load_dwordx4 v[2:5], v[166:167], off offset:3072
	v_sub_u32_e32 v49, v146, v48
	v_cmp_gt_u32_e32 vcc, 16, v49
	v_add_u32_e32 v50, 1, v49
	v_sub_u32_e32 v48, v147, v48
	v_cndmask_b32_e64 v192, v236, 0, vcc
	v_cmp_gt_u32_e32 vcc, 16, v50
	v_add_u32_e32 v50, 2, v49
	s_lshl_b64 s[12:13], s[12:13], 7
	v_cndmask_b32_e64 v193, v236, 0, vcc
	v_cmp_gt_u32_e32 vcc, 16, v50
	v_add_u32_e32 v50, 3, v49
	s_add_u32 s12, s11, s12
	v_cndmask_b32_e64 v194, v236, 0, vcc
	v_cmp_gt_u32_e32 vcc, 16, v50
	v_add_u32_e32 v50, 4, v49
	s_addc_u32 s13, 0, s13
	v_cndmask_b32_e64 v195, v236, 0, vcc
	v_cmp_gt_u32_e32 vcc, 16, v50
	v_add_u32_e32 v50, 5, v49
	v_add_u32_e32 v0, s20, v0
	v_cndmask_b32_e64 v196, v236, 0, vcc
	v_cmp_gt_u32_e32 vcc, 16, v50
	v_add_u32_e32 v50, 6, v49
	v_lshl_add_u64 v[168:169], v[162:163], 0, s[12:13]
	v_cndmask_b32_e64 v197, v236, 0, vcc
	v_cmp_gt_u32_e32 vcc, 16, v50
	v_add_u32_e32 v50, 7, v49
	v_lshl_add_u64 v[170:171], v[164:165], 0, s[12:13]
	v_cndmask_b32_e64 v198, v236, 0, vcc
	v_cmp_gt_u32_e32 vcc, 16, v50
	v_add_u32_e32 v50, 8, v49
	s_mov_b32 s11, 0
	v_cndmask_b32_e64 v199, v236, 0, vcc
	v_cmp_gt_u32_e32 vcc, 16, v50
	v_add_u32_e32 v50, 9, v49
	s_movk_i32 s23, 0x1000
	v_cndmask_b32_e64 v200, v236, 0, vcc
	v_cmp_gt_u32_e32 vcc, 16, v50
	v_add_u32_e32 v50, 10, v49
	s_nop 0
	v_cndmask_b32_e64 v201, v236, 0, vcc
	v_cmp_gt_u32_e32 vcc, 16, v50
	v_add_u32_e32 v50, 11, v49
	s_nop 0
	v_cndmask_b32_e64 v202, v236, 0, vcc
	v_cmp_gt_u32_e32 vcc, 16, v50
	v_add_u32_e32 v50, 12, v49
	s_nop 0
	v_cndmask_b32_e64 v203, v236, 0, vcc
	v_cmp_gt_u32_e32 vcc, 16, v50
	v_add_u32_e32 v50, 13, v49
	s_nop 0
	v_cndmask_b32_e64 v204, v236, 0, vcc
	v_cmp_gt_u32_e32 vcc, 16, v50
	v_add_u32_e32 v50, 14, v49
	v_add_u32_e32 v49, 15, v49
	v_cndmask_b32_e64 v205, v236, 0, vcc
	v_cmp_gt_u32_e32 vcc, 16, v50
	s_nop 1
	v_cndmask_b32_e64 v206, v236, 0, vcc
	v_cmp_gt_u32_e32 vcc, 16, v49
	v_add_u32_e32 v49, 1, v48
	s_nop 0
	v_cndmask_b32_e64 v207, v236, 0, vcc
	v_cmp_gt_u32_e32 vcc, 16, v48
	s_nop 1
	v_cndmask_b32_e64 v208, v236, 0, vcc
	v_cmp_gt_u32_e32 vcc, 16, v49
	v_add_u32_e32 v49, 2, v48
	s_nop 0
	v_cndmask_b32_e64 v209, v236, 0, vcc
	v_cmp_gt_u32_e32 vcc, 16, v49
	v_add_u32_e32 v49, 3, v48
	s_nop 0
	v_cndmask_b32_e64 v210, v236, 0, vcc
	v_cmp_gt_u32_e32 vcc, 16, v49
	v_add_u32_e32 v49, 4, v48
	s_nop 0
	v_cndmask_b32_e64 v211, v236, 0, vcc
	v_cmp_gt_u32_e32 vcc, 16, v49
	v_add_u32_e32 v49, 5, v48
	s_nop 0
	v_cndmask_b32_e64 v212, v236, 0, vcc
	v_cmp_gt_u32_e32 vcc, 16, v49
	v_add_u32_e32 v49, 6, v48
	s_nop 0
	v_cndmask_b32_e64 v213, v236, 0, vcc
	v_cmp_gt_u32_e32 vcc, 16, v49
	v_add_u32_e32 v49, 7, v48
	s_nop 0
	v_cndmask_b32_e64 v214, v236, 0, vcc
	v_cmp_gt_u32_e32 vcc, 16, v49
	v_add_u32_e32 v49, 8, v48
	s_nop 0
	v_cndmask_b32_e64 v215, v236, 0, vcc
	v_cmp_gt_u32_e32 vcc, 16, v49
	v_add_u32_e32 v49, 9, v48
	s_nop 0
	v_cndmask_b32_e64 v216, v236, 0, vcc
	v_cmp_gt_u32_e32 vcc, 16, v49
	v_add_u32_e32 v49, 10, v48
	s_nop 0
	v_cndmask_b32_e64 v217, v236, 0, vcc
	v_cmp_gt_u32_e32 vcc, 16, v49
	v_add_u32_e32 v49, 11, v48
	s_nop 0
	v_cndmask_b32_e64 v218, v236, 0, vcc
	v_cmp_gt_u32_e32 vcc, 16, v49
	v_add_u32_e32 v49, 12, v48
	s_nop 0
	v_cndmask_b32_e64 v219, v236, 0, vcc
	v_cmp_gt_u32_e32 vcc, 16, v49
	v_add_u32_e32 v49, 13, v48
	s_nop 0
	v_cndmask_b32_e64 v220, v236, 0, vcc
	v_cmp_gt_u32_e32 vcc, 16, v49
	v_add_u32_e32 v49, 14, v48
	v_add_u32_e32 v48, 15, v48
	v_cndmask_b32_e64 v221, v236, 0, vcc
	v_cmp_gt_u32_e32 vcc, 16, v49
	s_nop 1
	v_cndmask_b32_e64 v222, v236, 0, vcc
	v_cmp_gt_u32_e32 vcc, 16, v48
	s_nop 1
	v_cndmask_b32_e64 v223, v236, 0, vcc
	v_sub_f32_e32 v192, v192, v172
	v_sub_f32_e32 v193, v193, v172
	v_sub_f32_e32 v194, v194, v172
	v_sub_f32_e32 v195, v195, v172
	v_sub_f32_e32 v196, v196, v172
	v_sub_f32_e32 v197, v197, v172
	v_sub_f32_e32 v198, v198, v172
	v_sub_f32_e32 v199, v199, v172
	v_sub_f32_e32 v200, v200, v172
	v_sub_f32_e32 v201, v201, v172
	v_sub_f32_e32 v202, v202, v172
	v_sub_f32_e32 v203, v203, v172
	v_sub_f32_e32 v204, v204, v172
	v_sub_f32_e32 v205, v205, v172
	v_sub_f32_e32 v206, v206, v172
	v_sub_f32_e32 v207, v207, v172
	v_sub_f32_e32 v208, v208, v172
	v_sub_f32_e32 v209, v209, v172
	v_sub_f32_e32 v210, v210, v172
	v_sub_f32_e32 v211, v211, v172
	v_sub_f32_e32 v212, v212, v172
	v_sub_f32_e32 v213, v213, v172
	v_sub_f32_e32 v214, v214, v172
	v_sub_f32_e32 v215, v215, v172
	v_sub_f32_e32 v216, v216, v172
	v_sub_f32_e32 v217, v217, v172
	v_sub_f32_e32 v218, v218, v172
	v_sub_f32_e32 v219, v219, v172
	v_sub_f32_e32 v220, v220, v172
	v_sub_f32_e32 v221, v221, v172
	v_sub_f32_e32 v222, v222, v172
	v_sub_f32_e32 v223, v223, v172
	s_nop 1
	s_branch .LBB0_621
.LBB0_620:
	v_exp_f32_e32 v56, v123
	v_exp_f32_e32 v57, v122
	v_exp_f32_e32 v58, v121
	v_exp_f32_e32 v60, v120
	v_exp_f32_e32 v61, v119
	v_exp_f32_e32 v62, v118
	v_exp_f32_e32 v63, v117
	v_exp_f32_e32 v116, v116
	v_add_f32_e32 v59, 0, v56
	v_exp_f32_e32 v119, v53
	v_exp_f32_e32 v120, v52
	v_exp_f32_e32 v121, v51
	v_exp_f32_e32 v122, v50
	v_cvt_pk_bf16_f32 v50, v56, v57
	v_cvt_pk_bf16_f32 v51, v58, v60
	v_cvt_pk_bf16_f32 v52, v61, v62
	v_cvt_pk_bf16_f32 v53, v63, v116
	v_add_f32_e32 v59, v57, v59
	v_add_f32_e32 v59, v58, v59
	s_waitcnt vmcnt(11)
	v_mfma_f32_32x32x16_bf16 v[32:47], v[96:99], v[50:53], v[32:47]
	v_add_f32_e32 v58, v60, v59
	v_exp_f32_e32 v117, v55
	v_exp_f32_e32 v118, v54
	s_waitcnt vmcnt(9)
	v_mfma_f32_32x32x16_bf16 v[16:31], v[88:91], v[50:53], v[16:31]
	v_exp_f32_e32 v49, v49
	v_exp_f32_e32 v48, v48
	v_add_f32_e32 v58, v61, v58
	v_add_f32_e32 v58, v62, v58
	v_add_f32_e32 v58, v63, v58
	v_add_f32_e32 v58, v116, v58
	v_cvt_pk_bf16_f32 v54, v117, v118
	v_cvt_pk_bf16_f32 v55, v119, v120
	v_cvt_pk_bf16_f32 v56, v121, v122
	v_cvt_pk_bf16_f32 v57, v49, v48
	v_add_f32_e32 v58, v117, v58
	v_add_f32_e32 v58, v118, v58
	v_mfma_f32_32x32x16_bf16 v[32:47], v[92:95], v[54:57], v[32:47]
	v_add_f32_e32 v50, v119, v58
	v_add_f32_e32 v50, v120, v50
	v_add_f32_e32 v50, v121, v50
	v_add_f32_e32 v50, v122, v50
	v_add_f32_e32 v49, v49, v50
	v_add_f32_e32 v48, v48, v49
	s_add_i32 s11, s11, 2
	s_waitcnt vmcnt(8)
	v_mfma_f32_32x32x16_bf16 v[16:31], v[84:87], v[54:57], v[16:31]
	v_add_f32_e32 v224, v224, v48
	s_addk_i32 s23, 0x1000
	v_add_u32_e32 v0, 0x200, v0
	v_lshl_add_u64 v[168:169], v[168:169], 0, s[78:79]
	s_andn2_b64 vcc, exec, s[12:13]
	v_lshl_add_u64 v[170:171], v[170:171], 0, s[78:79]
	s_cbranch_vccz .LBB0_625
.LBB0_621:
	s_waitcnt vmcnt(7)
	v_mfma_f32_32x32x16_bf16 v[48:63], v[100:103], v[64:67], v[192:207]
	global_load_dwordx4 v[116:119], v[168:169], off offset:-2048
	global_load_dwordx4 v[120:123], v[168:169], off offset:-1024
	global_load_dwordx4 v[124:127], v[168:169], off
	global_load_dwordx4 v[128:131], v[168:169], off offset:1024
	ds_read2_b32 v[84:85], v0 offset1:1
	ds_read2_b32 v[86:87], v0 offset0:2 offset1:3
	ds_read2_b32 v[88:89], v0 offset0:4 offset1:5
	ds_read2_b32 v[90:91], v0 offset0:6 offset1:7
	ds_read2_b32 v[92:93], v0 offset0:8 offset1:9
	ds_read2_b32 v[94:95], v0 offset0:10 offset1:11
	ds_read2_b32 v[96:97], v0 offset0:12 offset1:13
	ds_read2_b32 v[98:99], v0 offset0:14 offset1:15
	s_waitcnt vmcnt(10)
	v_mfma_f32_32x32x16_bf16 v[48:63], v[104:107], v[68:71], v[48:63]
	s_waitcnt vmcnt(9)
	v_mfma_f32_32x32x16_bf16 v[48:63], v[108:111], v[72:75], v[48:63]
	s_waitcnt vmcnt(8)
	v_mfma_f32_32x32x16_bf16 v[48:63], v[112:115], v[76:79], v[48:63]
	s_waitcnt lgkmcnt(7)
	s_nop 10
	v_add_f32_e32 v107, v84, v48
	v_add_f32_e32 v106, v85, v49
	s_waitcnt lgkmcnt(6)
	v_add_f32_e32 v105, v86, v50
	v_add_f32_e32 v104, v87, v51
	s_waitcnt lgkmcnt(5)
	v_add_f32_e32 v103, v88, v52
	v_add_f32_e32 v102, v89, v53
	s_waitcnt lgkmcnt(4)
	v_add_f32_e32 v101, v90, v54
	v_add_f32_e32 v100, v91, v55
	s_waitcnt lgkmcnt(3)
	v_add_f32_e32 v55, v92, v56
	v_add_f32_e32 v54, v93, v57
	s_waitcnt lgkmcnt(2)
	v_add_f32_e32 v53, v94, v58
	v_add_f32_e32 v52, v95, v59
	s_waitcnt lgkmcnt(1)
	v_add_f32_e32 v51, v96, v60
	v_add_f32_e32 v50, v97, v61
	s_waitcnt lgkmcnt(0)
	v_add_f32_e32 v49, v98, v62
	v_add_f32_e32 v48, v99, v63
	global_load_dwordx4 v[96:99], v[170:171], off offset:-2048
	global_load_dwordx4 v[92:95], v[170:171], off offset:-1024
	global_load_dwordx4 v[88:91], v[170:171], off
	global_load_dwordx4 v[84:87], v[170:171], off offset:1024
	v_max_f32_e32 v56, v107, v106
	v_max3_f32 v56, v56, v105, v104
	v_max3_f32 v56, v56, v103, v102
	v_max3_f32 v56, v56, v101, v100
	v_max3_f32 v56, v56, v55, v54
	v_max3_f32 v56, v56, v53, v52
	v_max3_f32 v56, v56, v51, v50
	v_max3_f32 v56, v56, v49, v48
	v_mov_b32_e32 v57, v56
	s_nop 1
	v_permlane32_swap_b32_e32 v56, v57
	v_max_f32_e32 v57, v57, v57
	v_max_f32_e32 v56, v56, v56
	v_max_f32_e32 v56, v56, v57
	v_cmp_lt_f32_e32 vcc, s90, v56
	s_cbranch_vccz .LBB0_623
	v_max_f32_e32 v57, 0, v56
	v_exp_f32_e64 v56, -v57
	s_nop 0
	v_mul_f32_e32 v224, v224, v56
	v_pk_mul_f32 v[46:47], v[46:47], v[56:57] op_sel_hi:[1,0]
	v_pk_mul_f32 v[44:45], v[44:45], v[56:57] op_sel_hi:[1,0]
	v_pk_mul_f32 v[42:43], v[42:43], v[56:57] op_sel_hi:[1,0]
	v_pk_mul_f32 v[40:41], v[40:41], v[56:57] op_sel_hi:[1,0]
	v_pk_mul_f32 v[38:39], v[38:39], v[56:57] op_sel_hi:[1,0]
	v_pk_mul_f32 v[36:37], v[36:37], v[56:57] op_sel_hi:[1,0]
	v_pk_mul_f32 v[34:35], v[34:35], v[56:57] op_sel_hi:[1,0]
	v_pk_mul_f32 v[32:33], v[32:33], v[56:57] op_sel_hi:[1,0]
	v_pk_mul_f32 v[30:31], v[30:31], v[56:57] op_sel_hi:[1,0]
	v_pk_mul_f32 v[28:29], v[28:29], v[56:57] op_sel_hi:[1,0]
	v_pk_mul_f32 v[26:27], v[26:27], v[56:57] op_sel_hi:[1,0]
	v_pk_mul_f32 v[24:25], v[24:25], v[56:57] op_sel_hi:[1,0]
	v_pk_mul_f32 v[22:23], v[22:23], v[56:57] op_sel_hi:[1,0]
	v_pk_mul_f32 v[20:21], v[20:21], v[56:57] op_sel_hi:[1,0]
	v_pk_mul_f32 v[18:19], v[18:19], v[56:57] op_sel_hi:[1,0]
	v_pk_mul_f32 v[16:17], v[16:17], v[56:57] op_sel_hi:[1,0]
	v_sub_f32_e32 v107, v107, v57
	v_sub_f32_e32 v106, v106, v57
	v_sub_f32_e32 v105, v105, v57
	v_sub_f32_e32 v104, v104, v57
	v_sub_f32_e32 v103, v103, v57
	v_sub_f32_e32 v102, v102, v57
	v_sub_f32_e32 v101, v101, v57
	v_sub_f32_e32 v100, v100, v57
	v_sub_f32_e32 v55, v55, v57
	v_sub_f32_e32 v54, v54, v57
	v_sub_f32_e32 v53, v53, v57
	v_sub_f32_e32 v52, v52, v57
	v_sub_f32_e32 v51, v51, v57
	v_sub_f32_e32 v50, v50, v57
	v_sub_f32_e32 v49, v49, v57
	v_sub_f32_e32 v48, v48, v57
	v_sub_f32_e32 v192, v192, v57
	v_sub_f32_e32 v193, v193, v57
	v_sub_f32_e32 v194, v194, v57
	v_sub_f32_e32 v195, v195, v57
	v_sub_f32_e32 v196, v196, v57
	v_sub_f32_e32 v197, v197, v57
	v_sub_f32_e32 v198, v198, v57
	v_sub_f32_e32 v199, v199, v57
	v_sub_f32_e32 v200, v200, v57
	v_sub_f32_e32 v201, v201, v57
	v_sub_f32_e32 v202, v202, v57
	v_sub_f32_e32 v203, v203, v57
	v_sub_f32_e32 v204, v204, v57
	v_sub_f32_e32 v205, v205, v57
	v_sub_f32_e32 v206, v206, v57
	v_sub_f32_e32 v207, v207, v57
	v_sub_f32_e32 v208, v208, v57
	v_sub_f32_e32 v209, v209, v57
	v_sub_f32_e32 v210, v210, v57
	v_sub_f32_e32 v211, v211, v57
	v_sub_f32_e32 v212, v212, v57
	v_sub_f32_e32 v213, v213, v57
	v_sub_f32_e32 v214, v214, v57
	v_sub_f32_e32 v215, v215, v57
	v_sub_f32_e32 v216, v216, v57
	v_sub_f32_e32 v217, v217, v57
	v_sub_f32_e32 v218, v218, v57
	v_sub_f32_e32 v219, v219, v57
	v_sub_f32_e32 v220, v220, v57
	v_sub_f32_e32 v221, v221, v57
	v_sub_f32_e32 v222, v222, v57
	v_sub_f32_e32 v223, v223, v57
.LBB0_623:
	v_exp_f32_e32 v56, v107
	v_exp_f32_e32 v58, v106
	v_exp_f32_e32 v59, v105
	v_exp_f32_e32 v60, v104
	v_add_f32_e32 v57, 0, v56
	v_exp_f32_e32 v61, v103
	v_add_f32_e32 v57, v58, v57
	v_exp_f32_e32 v62, v102
	v_add_f32_e32 v57, v59, v57
	v_exp_f32_e32 v63, v101
	v_add_f32_e32 v57, v60, v57
	v_exp_f32_e32 v100, v100
	v_add_f32_e32 v57, v61, v57
	v_exp_f32_e32 v55, v55
	v_add_f32_e32 v57, v62, v57
	v_exp_f32_e32 v54, v54
	v_add_f32_e32 v57, v63, v57
	v_exp_f32_e32 v53, v53
	v_add_f32_e32 v57, v100, v57
	v_exp_f32_e32 v101, v52
	v_add_f32_e32 v57, v55, v57
	v_add_f32_e32 v57, v54, v57
	v_add_f32_e32 v57, v53, v57
	v_add_f32_e32 v52, v101, v57
	v_exp_f32_e32 v57, v51
	v_exp_f32_e32 v102, v50
	v_exp_f32_e32 v103, v49
	v_exp_f32_e32 v104, v48
	v_add_f32_e32 v51, v57, v52
	v_add_f32_e32 v50, v102, v51
	v_add_f32_e32 v49, v103, v50
	v_add_f32_e32 v48, v104, v49
	v_add_f32_e32 v224, v224, v48
	v_cvt_pk_bf16_f32 v48, v56, v58
	v_cvt_pk_bf16_f32 v49, v59, v60
	v_cvt_pk_bf16_f32 v50, v61, v62
	v_cvt_pk_bf16_f32 v51, v63, v100
	v_cvt_pk_bf16_f32 v52, v55, v54
	v_cvt_pk_bf16_f32 v53, v53, v101
	s_waitcnt vmcnt(11)
	v_mfma_f32_32x32x16_bf16 v[32:47], v[80:83], v[48:51], v[32:47]
	v_cvt_pk_bf16_f32 v54, v57, v102
	v_cvt_pk_bf16_f32 v55, v103, v104
	s_cmp_gt_u32 s11, 13
	s_cselect_b64 s[12:13], -1, 0
	s_cmp_lt_u32 s11, 14
	s_cselect_b32 s70, s23, 0
	s_lshl_b64 s[14:15], s[70:71], 1
	s_waitcnt vmcnt(9)
	v_mfma_f32_32x32x16_bf16 v[16:31], v[10:13], v[48:51], v[16:31]
	v_mfma_f32_32x32x16_bf16 v[32:47], v[6:9], v[52:55], v[32:47]
	s_waitcnt vmcnt(8)
	v_mfma_f32_32x32x16_bf16 v[16:31], v[2:5], v[52:55], v[16:31]
	v_lshl_add_u64 v[2:3], v[14:15], 0, s[14:15]
	global_load_dwordx4 v[100:103], v[2:3], off
	global_load_dwordx4 v[104:107], v[2:3], off offset:1024
	global_load_dwordx4 v[108:111], v[2:3], off offset:2048
	global_load_dwordx4 v[112:115], v[2:3], off offset:3072
	ds_read2_b32 v[2:3], v0 offset0:32 offset1:33
	ds_read2_b32 v[4:5], v0 offset0:34 offset1:35
	ds_read2_b32 v[6:7], v0 offset0:36 offset1:37
	ds_read2_b32 v[8:9], v0 offset0:38 offset1:39
	ds_read2_b32 v[10:11], v0 offset0:40 offset1:41
	ds_read2_b32 v[12:13], v0 offset0:42 offset1:43
	ds_read2_b32 v[80:81], v0 offset0:44 offset1:45
	ds_read2_b32 v[82:83], v0 offset0:46 offset1:47
	s_waitcnt vmcnt(11)
	v_mfma_f32_32x32x16_bf16 v[48:63], v[116:119], v[64:67], v[208:223]
	s_waitcnt vmcnt(10)
	v_mfma_f32_32x32x16_bf16 v[48:63], v[120:123], v[68:71], v[48:63]
	s_waitcnt vmcnt(9)
	v_mfma_f32_32x32x16_bf16 v[48:63], v[124:127], v[72:75], v[48:63]
	s_waitcnt vmcnt(8)
	v_mfma_f32_32x32x16_bf16 v[48:63], v[128:131], v[76:79], v[48:63]
	s_waitcnt lgkmcnt(7)
	s_nop 10
	v_add_f32_e32 v123, v2, v48
	v_add_f32_e32 v122, v3, v49
	s_waitcnt lgkmcnt(6)
	v_add_f32_e32 v121, v4, v50
	v_add_f32_e32 v120, v5, v51
	s_waitcnt lgkmcnt(5)
	v_add_f32_e32 v119, v6, v52
	v_add_f32_e32 v118, v7, v53
	s_waitcnt lgkmcnt(4)
	v_add_f32_e32 v117, v8, v54
	v_add_f32_e32 v116, v9, v55
	s_waitcnt lgkmcnt(3)
	v_add_f32_e32 v55, v10, v56
	v_add_f32_e32 v54, v11, v57
	s_waitcnt lgkmcnt(2)
	v_add_f32_e32 v53, v12, v58
	v_add_f32_e32 v52, v13, v59
	s_waitcnt lgkmcnt(1)
	v_add_f32_e32 v51, v80, v60
	v_add_f32_e32 v50, v81, v61
	s_waitcnt lgkmcnt(0)
	v_add_f32_e32 v49, v82, v62
	v_add_f32_e32 v48, v83, v63
	v_lshl_add_u64 v[2:3], v[166:167], 0, s[14:15]
	global_load_dwordx4 v[80:83], v[2:3], off
	global_load_dwordx4 v[6:9], v[2:3], off offset:1024
	global_load_dwordx4 v[10:13], v[2:3], off offset:2048
	s_nop 0
	global_load_dwordx4 v[2:5], v[2:3], off offset:3072
	v_max_f32_e32 v56, v123, v122
	v_max3_f32 v56, v56, v121, v120
	v_max3_f32 v56, v56, v119, v118
	v_max3_f32 v56, v56, v117, v116
	v_max3_f32 v56, v56, v55, v54
	v_max3_f32 v56, v56, v53, v52
	v_max3_f32 v56, v56, v51, v50
	v_max3_f32 v56, v56, v49, v48
	v_mov_b32_e32 v57, v56
	s_nop 1
	v_permlane32_swap_b32_e32 v56, v57
	v_max_f32_e32 v57, v57, v57
	v_max_f32_e32 v56, v56, v56
	v_max_f32_e32 v56, v56, v57
	v_cmp_lt_f32_e32 vcc, s90, v56
	s_cbranch_vccz .LBB0_620
	v_max_f32_e32 v57, 0, v56
	v_exp_f32_e64 v56, -v57
	s_nop 0
	v_mul_f32_e32 v224, v224, v56
	v_pk_mul_f32 v[46:47], v[46:47], v[56:57] op_sel_hi:[1,0]
	v_pk_mul_f32 v[44:45], v[44:45], v[56:57] op_sel_hi:[1,0]
	v_pk_mul_f32 v[42:43], v[42:43], v[56:57] op_sel_hi:[1,0]
	v_pk_mul_f32 v[40:41], v[40:41], v[56:57] op_sel_hi:[1,0]
	v_pk_mul_f32 v[38:39], v[38:39], v[56:57] op_sel_hi:[1,0]
	v_pk_mul_f32 v[36:37], v[36:37], v[56:57] op_sel_hi:[1,0]
	v_pk_mul_f32 v[34:35], v[34:35], v[56:57] op_sel_hi:[1,0]
	v_pk_mul_f32 v[32:33], v[32:33], v[56:57] op_sel_hi:[1,0]
	v_pk_mul_f32 v[30:31], v[30:31], v[56:57] op_sel_hi:[1,0]
	v_pk_mul_f32 v[28:29], v[28:29], v[56:57] op_sel_hi:[1,0]
	v_pk_mul_f32 v[26:27], v[26:27], v[56:57] op_sel_hi:[1,0]
	v_pk_mul_f32 v[24:25], v[24:25], v[56:57] op_sel_hi:[1,0]
	v_pk_mul_f32 v[22:23], v[22:23], v[56:57] op_sel_hi:[1,0]
	v_pk_mul_f32 v[20:21], v[20:21], v[56:57] op_sel_hi:[1,0]
	v_pk_mul_f32 v[18:19], v[18:19], v[56:57] op_sel_hi:[1,0]
	v_pk_mul_f32 v[16:17], v[16:17], v[56:57] op_sel_hi:[1,0]
	v_sub_f32_e32 v123, v123, v57
	v_sub_f32_e32 v122, v122, v57
	v_sub_f32_e32 v121, v121, v57
	v_sub_f32_e32 v120, v120, v57
	v_sub_f32_e32 v119, v119, v57
	v_sub_f32_e32 v118, v118, v57
	v_sub_f32_e32 v117, v117, v57
	v_sub_f32_e32 v116, v116, v57
	v_sub_f32_e32 v55, v55, v57
	v_sub_f32_e32 v54, v54, v57
	v_sub_f32_e32 v53, v53, v57
	v_sub_f32_e32 v52, v52, v57
	v_sub_f32_e32 v51, v51, v57
	v_sub_f32_e32 v50, v50, v57
	v_sub_f32_e32 v49, v49, v57
	v_sub_f32_e32 v48, v48, v57
	v_sub_f32_e32 v192, v192, v57
	v_sub_f32_e32 v193, v193, v57
	v_sub_f32_e32 v194, v194, v57
	v_sub_f32_e32 v195, v195, v57
	v_sub_f32_e32 v196, v196, v57
	v_sub_f32_e32 v197, v197, v57
	v_sub_f32_e32 v198, v198, v57
	v_sub_f32_e32 v199, v199, v57
	v_sub_f32_e32 v200, v200, v57
	v_sub_f32_e32 v201, v201, v57
	v_sub_f32_e32 v202, v202, v57
	v_sub_f32_e32 v203, v203, v57
	v_sub_f32_e32 v204, v204, v57
	v_sub_f32_e32 v205, v205, v57
	v_sub_f32_e32 v206, v206, v57
	v_sub_f32_e32 v207, v207, v57
	v_sub_f32_e32 v208, v208, v57
	v_sub_f32_e32 v209, v209, v57
	v_sub_f32_e32 v210, v210, v57
	v_sub_f32_e32 v211, v211, v57
	v_sub_f32_e32 v212, v212, v57
	v_sub_f32_e32 v213, v213, v57
	v_sub_f32_e32 v214, v214, v57
	v_sub_f32_e32 v215, v215, v57
	v_sub_f32_e32 v216, v216, v57
	v_sub_f32_e32 v217, v217, v57
	v_sub_f32_e32 v218, v218, v57
	v_sub_f32_e32 v219, v219, v57
	v_sub_f32_e32 v220, v220, v57
	v_sub_f32_e32 v221, v221, v57
	v_sub_f32_e32 v222, v222, v57
	v_sub_f32_e32 v223, v223, v57
	s_branch .LBB0_620
.LBB0_625:
	v_mov_b32_e32 v0, v224
	s_nop 1
	v_permlane32_swap_b32_e32 v224, v0
	v_add_f32_e32 v0, v224, v0
	s_waitcnt vmcnt(0)
	global_load_dwordx4 v[64:67], v[142:143], off offset:1024
	global_load_dwordx4 v[68:71], v[142:143], off offset:1056
	global_load_dwordx4 v[72:75], v[142:143], off offset:1088
	global_load_dwordx4 v[76:79], v[142:143], off offset:1120
	global_load_dwordx4 v[116:119], v[142:143], off offset:1152
	global_load_dwordx4 v[120:123], v[142:143], off offset:1184
	global_load_dwordx4 v[124:127], v[142:143], off offset:1216
	global_load_dwordx4 v[128:131], v[142:143], off offset:1248
	v_div_scale_f32 v2, s[12:13], v0, v0, 1.0
	v_rcp_f32_e32 v3, v2
	s_nop 0
	v_fma_f32 v4, -v2, v3, 1.0
	v_fmac_f32_e32 v3, v4, v3
	v_div_scale_f32 v4, vcc, 1.0, v0, 1.0
	v_mul_f32_e32 v5, v4, v3
	v_fma_f32 v6, -v2, v5, v4
	v_fmac_f32_e32 v5, v6, v3
	v_fma_f32 v2, -v2, v5, v4
	v_div_fmas_f32 v2, v2, v3, v5
	v_div_fixup_f32 v0, v2, v0, 1.0
	v_pk_mul_f32 v[8:9], v[16:17], v[0:1] op_sel_hi:[1,0]
	v_pk_mul_f32 v[48:49], v[32:33], v[0:1] op_sel_hi:[1,0]
	v_pk_mul_f32 v[2:3], v[8:9], v[8:9]
	v_pk_mul_f32 v[10:11], v[18:19], v[0:1] op_sel_hi:[1,0]
	v_pk_fma_f32 v[2:3], v[48:49], v[48:49], v[2:3]
	v_pk_mul_f32 v[34:35], v[34:35], v[0:1] op_sel_hi:[1,0]
	v_pk_mul_f32 v[4:5], v[10:11], v[10:11]
	v_pk_add_f32 v[2:3], v[2:3], v[2:3] op_sel:[0,1] op_sel_hi:[1,0]
	v_pk_fma_f32 v[4:5], v[34:35], v[34:35], v[4:5]
	v_pk_mul_f32 v[18:19], v[36:37], v[0:1] op_sel_hi:[1,0]
	v_pk_add_f32 v[2:3], v[4:5], v[2:3]
	v_pk_mul_f32 v[12:13], v[22:23], v[0:1] op_sel_hi:[1,0]
	v_pk_add_f32 v[4:5], v[4:5], v[2:3] op_sel:[1,0] op_sel_hi:[0,1]
	v_pk_mul_f32 v[2:3], v[20:21], v[0:1] op_sel_hi:[1,0]
	v_pk_mul_f32 v[32:33], v[38:39], v[0:1] op_sel_hi:[1,0]
	v_pk_mul_f32 v[6:7], v[2:3], v[2:3]
	v_pk_mul_f32 v[20:21], v[40:41], v[0:1] op_sel_hi:[1,0]
	v_pk_fma_f32 v[6:7], v[18:19], v[18:19], v[6:7]
	v_pk_mul_f32 v[22:23], v[44:45], v[0:1] op_sel_hi:[1,0]
	v_pk_add_f32 v[4:5], v[6:7], v[4:5]
	s_nop 0
	v_pk_add_f32 v[4:5], v[6:7], v[4:5] op_sel:[1,0] op_sel_hi:[0,1]
	v_pk_mul_f32 v[6:7], v[12:13], v[12:13]
	s_nop 0
	v_pk_fma_f32 v[6:7], v[32:33], v[32:33], v[6:7]
	s_nop 0
	v_pk_add_f32 v[4:5], v[6:7], v[4:5]
	s_nop 0
	v_pk_add_f32 v[6:7], v[6:7], v[4:5] op_sel:[1,0] op_sel_hi:[0,1]
	v_pk_mul_f32 v[4:5], v[24:25], v[0:1] op_sel_hi:[1,0]
	v_pk_mul_f32 v[24:25], v[42:43], v[0:1] op_sel_hi:[1,0]
	v_pk_mul_f32 v[14:15], v[4:5], v[4:5]
	s_nop 0
	v_pk_fma_f32 v[14:15], v[20:21], v[20:21], v[14:15]
	s_nop 0
	v_pk_add_f32 v[6:7], v[14:15], v[6:7]
	s_nop 0
	v_pk_add_f32 v[6:7], v[14:15], v[6:7] op_sel:[1,0] op_sel_hi:[0,1]
	v_pk_mul_f32 v[14:15], v[26:27], v[0:1] op_sel_hi:[1,0]
	s_nop 0
	v_pk_mul_f32 v[16:17], v[14:15], v[14:15]
	s_nop 0
	v_pk_fma_f32 v[16:17], v[24:25], v[24:25], v[16:17]
	s_nop 0
	v_pk_add_f32 v[6:7], v[16:17], v[6:7]
	s_nop 0
	v_pk_add_f32 v[16:17], v[16:17], v[6:7] op_sel:[1,0] op_sel_hi:[0,1]
	v_pk_mul_f32 v[6:7], v[28:29], v[0:1] op_sel_hi:[1,0]
	s_nop 0
	v_pk_mul_f32 v[26:27], v[6:7], v[6:7]
	s_nop 0
	v_pk_fma_f32 v[26:27], v[22:23], v[22:23], v[26:27]
	s_nop 0
	v_pk_add_f32 v[16:17], v[26:27], v[16:17]
	s_nop 0
	v_pk_add_f32 v[28:29], v[26:27], v[16:17] op_sel:[1,0] op_sel_hi:[0,1]
	v_pk_mul_f32 v[16:17], v[30:31], v[0:1] op_sel_hi:[1,0]
	v_pk_mul_f32 v[26:27], v[46:47], v[0:1] op_sel_hi:[1,0]
	v_pk_mul_f32 v[30:31], v[16:17], v[16:17]
	s_nop 0
	v_pk_fma_f32 v[30:31], v[26:27], v[26:27], v[30:31]
	s_nop 0
	v_pk_add_f32 v[28:29], v[30:31], v[28:29]
	s_nop 0
	v_pk_add_f32 v[28:29], v[30:31], v[28:29] op_sel:[1,0] op_sel_hi:[0,1]
	v_mov_b32_e32 v0, v28
	s_nop 1
	v_permlane32_swap_b32_e32 v28, v0
	s_and_saveexec_b64 s[12:13], s[4:5]
	s_cbranch_execz .LBB0_606
	v_add_f32_e32 v0, v28, v0
	ds_write_b32 v133, v0 offset:61440
	s_branch .LBB0_606
